# prompt loop: this wave's Q fragments stay in registers (no per-tile LDS re-read); exp, row-sum and bf16 pack streamed per pair so scores stay intact for the rare exact path
# speedup vs baseline: 1.0060x; 1.0060x over previous
.LBB0_819:
	v_max3_f32 v2, v4, v20, v5
	v_max3_f32 v49, v21, v6, v22
	s_ashr_i32 s21, s4, 1
	v_max3_f32 v2, v2, v7, v23
	v_max3_f32 v49, v49, v8, v24
	s_lshl_b32 s23, s35, 2
	v_max3_f32 v2, v2, v9, v25
	v_max3_f32 v49, v49, v10, v26
	v_and_b32_e32 v88, 16, v48
	v_max3_f32 v2, v2, v11, v27
	v_max3_f32 v49, v49, v12, v28
	s_mov_b32 s4, 1
	v_max3_f32 v2, v2, v13, v29
	v_max3_f32 v49, v49, v14, v30
	s_nop 0
	v_max3_f32 v2, v2, v15, v31
	v_max3_f32 v49, v49, v16, v32
	s_nop 0
	v_max3_f32 v2, v2, v17, v33
	v_max3_f32 v49, v49, v18, v34
	s_nop 0
	v_max3_f32 v2, v2, v49, v19
	s_nop 0
	v_max_f32_e32 v49, v35, v35
	v_max_f32_e32 v2, v2, v2
	v_max_f32_e32 v2, v2, v49
	v_mov_b32_e32 v49, v2
	s_nop 1
	v_permlane32_swap_b32_e32 v2, v49
	v_max_f32_e32 v49, v49, v49
	v_max_f32_e32 v2, v2, v2
	v_max_f32_e32 v2, v2, v49
	v_mul_f32_e32 v2, 0x3f800000, v2
	v_cmp_neq_f32_e32 vcc, s78, v2
	s_cmp_eq_u64 vcc, 0
	v_max_f32_e32 v49, 0xff800000, v2
	s_cselect_b64 vcc, -1, 0
	v_cndmask_b32_e32 v159, v49, v230, vcc
	v_fma_f32 v2, v4, 1.0, -v159
	v_exp_f32_e32 v84, v2
	v_fma_f32 v2, v20, 1.0, -v159
	v_exp_f32_e32 v85, v2
	v_fma_f32 v2, v5, 1.0, -v159
	v_fma_f32 v4, v21, 1.0, -v159
	v_exp_f32_e32 v2, v2
	v_exp_f32_e32 v20, v4
	v_add_f32_e32 v21, v85, v84
	v_cvt_pk_bf16_f32 v144, v84, v2
	v_pk_add_f32 v[4:5], v[20:21], v[2:3]
	v_cvt_pk_bf16_f32 v136, v85, v20
	v_pk_add_f32 v[50:51], v[4:5], v[4:5] op_sel_hi:[0,1]
	v_fma_f32 v4, v6, 1.0, -v159
	v_exp_f32_e32 v21, v4
	v_fma_f32 v4, v22, 1.0, -v159
	v_exp_f32_e32 v86, v4
	v_fma_f32 v4, v7, 1.0, -v159
	v_exp_f32_e32 v50, v4
	v_fma_f32 v4, v23, 1.0, -v159
	v_exp_f32_e32 v6, v4
	v_add_f32_e32 v7, v86, v21
	v_cvt_pk_bf16_f32 v145, v21, v50
	v_pk_add_f32 v[4:5], v[6:7], v[50:51]
	s_nop 0
	v_pk_add_f32 v[22:23], v[4:5], v[4:5] op_sel_hi:[0,1]
	v_fma_f32 v4, v8, 1.0, -v159
	v_exp_f32_e32 v7, v4
	v_fma_f32 v4, v24, 1.0, -v159
	v_exp_f32_e32 v51, v4
	v_fma_f32 v4, v9, 1.0, -v159
	v_exp_f32_e32 v22, v4
	v_fma_f32 v4, v25, 1.0, -v159
	v_exp_f32_e32 v8, v4
	v_add_f32_e32 v9, v51, v7
	v_cvt_pk_bf16_f32 v146, v7, v22
	v_cvt_pk_bf16_f32 v137, v86, v6
	v_pk_add_f32 v[4:5], v[8:9], v[22:23]
	v_cvt_pk_bf16_f32 v138, v51, v8
	v_pk_add_f32 v[24:25], v[4:5], v[4:5] op_sel_hi:[0,1]
	v_fma_f32 v4, v10, 1.0, -v159
	v_exp_f32_e32 v9, v4
	v_fma_f32 v4, v26, 1.0, -v159
	v_exp_f32_e32 v23, v4
	v_fma_f32 v4, v11, 1.0, -v159
	v_exp_f32_e32 v24, v4
	v_fma_f32 v4, v27, 1.0, -v159
	v_exp_f32_e32 v10, v4
	v_lshrrev_b32_e32 v4, 2, v48
	v_add_f32_e32 v11, v23, v9
	v_and_or_b32 v87, v4, 3, v154
	v_pk_add_f32 v[4:5], v[10:11], v[24:25]
	v_lshlrev_b32_e32 v48, 2, v48
	v_pk_add_f32 v[26:27], v[4:5], v[4:5] op_sel_hi:[0,1]
	v_fma_f32 v4, v12, 1.0, -v159
	v_exp_f32_e32 v11, v4
	v_fma_f32 v4, v28, 1.0, -v159
	v_exp_f32_e32 v25, v4
	v_fma_f32 v4, v13, 1.0, -v159
	v_exp_f32_e32 v26, v4
	v_fma_f32 v4, v29, 1.0, -v159
	v_exp_f32_e32 v12, v4
	v_add_f32_e32 v13, v25, v11
	v_mul_u32_u24_e32 v87, 0xc0, v87
	v_cvt_pk_bf16_f32 v147, v9, v24
	v_pk_add_f32 v[4:5], v[12:13], v[26:27]
	v_cvt_pk_bf16_f32 v140, v11, v26
	v_pk_add_f32 v[28:29], v[4:5], v[4:5] op_sel_hi:[0,1]
	v_fma_f32 v4, v14, 1.0, -v159
	v_exp_f32_e32 v13, v4
	v_fma_f32 v4, v30, 1.0, -v159
	v_exp_f32_e32 v27, v4
	v_fma_f32 v4, v15, 1.0, -v159
	v_exp_f32_e32 v28, v4
	v_fma_f32 v4, v31, 1.0, -v159
	v_exp_f32_e32 v14, v4
	v_add_f32_e32 v15, v27, v13
	v_cvt_pk_bf16_f32 v141, v13, v28
	v_cvt_pk_bf16_f32 v139, v23, v10
	v_pk_add_f32 v[4:5], v[14:15], v[28:29]
	v_cvt_pk_bf16_f32 v132, v25, v12
	v_pk_add_f32 v[30:31], v[4:5], v[4:5] op_sel_hi:[0,1]
	v_fma_f32 v4, v16, 1.0, -v159
	v_exp_f32_e32 v15, v4
	v_fma_f32 v4, v32, 1.0, -v159
	v_exp_f32_e32 v29, v4
	v_fma_f32 v4, v17, 1.0, -v159
	v_exp_f32_e32 v30, v4
	v_fma_f32 v4, v33, 1.0, -v159
	v_exp_f32_e32 v16, v4
	v_and_or_b32 v4, v48, 12, v88
	v_add_f32_e32 v17, v29, v15
	v_lshl_or_b32 v162, v4, 1, v87
	v_pk_add_f32 v[4:5], v[16:17], v[30:31]
	v_cvt_pk_bf16_f32 v142, v15, v30
	v_pk_add_f32 v[32:33], v[4:5], v[4:5] op_sel_hi:[0,1]
	v_fma_f32 v4, v18, 1.0, -v159
	v_exp_f32_e32 v17, v4
	v_fma_f32 v4, v34, 1.0, -v159
	v_exp_f32_e32 v31, v4
	v_fma_f32 v4, v19, 1.0, -v159
	v_exp_f32_e32 v32, v4
	v_fma_f32 v4, v35, 1.0, -v159
	v_exp_f32_e32 v18, v4
	v_sub_f32_e32 v4, 0xff800000, v49
	v_exp_f32_e32 v34, v4
	v_add_f32_e32 v19, v31, v17
	v_pk_add_f32 v[4:5], v[18:19], v[32:33]
	v_cvt_pk_bf16_f32 v143, v17, v32
	v_add_f32_e32 v5, v4, v5
	v_mul_f32_e32 v4, 0, v34
	v_cndmask_b32_e64 v4, v4, 0, vcc
	v_add_f32_e32 v152, v4, v5
	v_cvt_pk_bf16_f32 v133, v27, v14
	v_cvt_pk_bf16_f32 v134, v29, v16
	v_cvt_pk_bf16_f32 v135, v31, v18
	v_mad_u64_u32 v[20:21], s[50:51], v45, s80, v[44:45]
	v_mov_b32_e32 v5, v4
	v_mov_b32_e32 v6, v4
	v_mov_b32_e32 v7, v4
	v_mov_b32_e32 v8, v4
	v_mov_b32_e32 v9, v4
	v_mov_b32_e32 v10, v4
	v_mov_b32_e32 v11, v4
	v_mov_b32_e32 v12, v4
	v_mov_b32_e32 v13, v4
	v_mov_b32_e32 v14, v4
	v_mov_b32_e32 v15, v4
	v_mov_b32_e32 v16, v4
	v_mov_b32_e32 v17, v4
	v_mov_b32_e32 v18, v4
	v_mov_b32_e32 v19, v4
	v_add_u32_e32 v151, 0, v20
	s_andn2_b64 vcc, exec, s[2:3]
	s_waitcnt vmcnt(1)
	ds_write_b128 v157, v[40:43]
	ds_write_b64 v158, v[46:47] offset:128
	s_waitcnt vmcnt(0)
	ds_write_b128 v151, v[36:39] offset:26624
	s_waitcnt lgkmcnt(0)
	s_barrier
	s_cbranch_vccnz .LBB0_859
	v_mov_b64_e32 v[34:35], v[18:19]
	v_mov_b64_e32 v[98:99], v[66:67]
	v_mov_b64_e32 v[36:37], v[68:69]
	s_add_i32 s50, s23, -1
	s_mov_b32 s51, 1
	s_mov_b32 s52, s68
	s_mov_b32 s53, s67
	v_mov_b64_e32 v[32:33], v[16:17]
	v_mov_b64_e32 v[30:31], v[14:15]
	v_mov_b64_e32 v[28:29], v[12:13]
	v_mov_b64_e32 v[26:27], v[10:11]
	v_mov_b64_e32 v[24:25], v[8:9]
	v_mov_b64_e32 v[22:23], v[6:7]
	v_mov_b64_e32 v[20:21], v[4:5]
	v_mov_b64_e32 v[96:97], v[64:65]
	v_mov_b64_e32 v[94:95], v[62:63]
	v_mov_b64_e32 v[92:93], v[60:61]
	v_mov_b64_e32 v[90:91], v[58:59]
	v_mov_b64_e32 v[88:89], v[56:57]
	v_mov_b64_e32 v[86:87], v[54:55]
	v_mov_b64_e32 v[84:85], v[52:53]
	v_mov_b64_e32 v[38:39], v[70:71]
	v_mov_b64_e32 v[40:41], v[72:73]
	v_mov_b64_e32 v[42:43], v[74:75]
	v_mov_b64_e32 v[44:45], v[76:77]
	v_mov_b64_e32 v[46:47], v[78:79]
	v_mov_b64_e32 v[48:49], v[80:81]
	v_mov_b64_e32 v[50:51], v[82:83]
	v_xor_b32_e32 v234, 0x80000000, v159
	v_xor_b32_e32 v235, 0x80000000, v159
	v_xor_b32_e32 v236, 0x80000000, v159
	v_xor_b32_e32 v237, 0x80000000, v159
	v_xor_b32_e32 v238, 0x80000000, v159
	v_xor_b32_e32 v239, 0x80000000, v159
	v_xor_b32_e32 v240, 0x80000000, v159
	v_xor_b32_e32 v241, 0x80000000, v159
	v_xor_b32_e32 v242, 0x80000000, v159
	v_xor_b32_e32 v243, 0x80000000, v159
	v_xor_b32_e32 v244, 0x80000000, v159
	v_xor_b32_e32 v245, 0x80000000, v159
	v_xor_b32_e32 v246, 0x80000000, v159
	v_xor_b32_e32 v247, 0x80000000, v159
	v_xor_b32_e32 v248, 0x80000000, v159
	v_xor_b32_e32 v249, 0x80000000, v159
	v_sub_f32_e32 v84, v84, v159
	v_sub_f32_e32 v36, v36, v159
	v_sub_f32_e32 v85, v85, v159
	v_sub_f32_e32 v37, v37, v159
	v_sub_f32_e32 v86, v86, v159
	v_sub_f32_e32 v38, v38, v159
	v_sub_f32_e32 v87, v87, v159
	v_sub_f32_e32 v39, v39, v159
	v_sub_f32_e32 v88, v88, v159
	v_sub_f32_e32 v40, v40, v159
	v_sub_f32_e32 v89, v89, v159
	v_sub_f32_e32 v41, v41, v159
	v_sub_f32_e32 v90, v90, v159
	v_sub_f32_e32 v42, v42, v159
	v_sub_f32_e32 v91, v91, v159
	v_sub_f32_e32 v43, v43, v159
	v_sub_f32_e32 v92, v92, v159
	v_sub_f32_e32 v44, v44, v159
	v_sub_f32_e32 v93, v93, v159
	v_sub_f32_e32 v45, v45, v159
	v_sub_f32_e32 v94, v94, v159
	v_sub_f32_e32 v46, v46, v159
	v_sub_f32_e32 v95, v95, v159
	v_sub_f32_e32 v47, v47, v159
	v_sub_f32_e32 v96, v96, v159
	v_sub_f32_e32 v48, v48, v159
	v_sub_f32_e32 v97, v97, v159
	v_sub_f32_e32 v49, v49, v159
	v_sub_f32_e32 v98, v98, v159
	v_sub_f32_e32 v50, v50, v159
	v_sub_f32_e32 v99, v99, v159
	v_sub_f32_e32 v51, v51, v159
	v_add_u32_e32 v163, 0, v162
	ds_read_b128 v[200:203], v156 offset:51200
	ds_read_b128 v[204:207], v156 offset:51232
	ds_read_b128 v[208:211], v156 offset:51264
	ds_read_b128 v[212:215], v156 offset:51296
	ds_read_b128 v[216:219], v156 offset:51328
	ds_read_b128 v[250:253], v156 offset:51360
	s_waitcnt lgkmcnt(0)
.LBB0_822:
	s_mov_b32 s5, 0
	s_add_i32 s2, s52, 0xfffff000
	buffer_load_dwordx2 v[108:109], v161, s[12:15], s2 offen
	s_add_i32 s3, s53, 0xfe020000
	buffer_load_dwordx4 v[104:107], v150, s[12:15], s3 offen
	s_add_i32 s4, s53, 0xfffe0000
	buffer_load_dwordx4 v[100:103], v150, s[12:15], s4 offen
	ds_read_b64_tr_b16 v[164:165], v162 offset:26624
	ds_read_b64_tr_b16 v[166:167], v162 offset:28160
	ds_read_b64_tr_b16 v[168:169], v162 offset:26688
	ds_read_b64_tr_b16 v[170:171], v162 offset:28224
	ds_read_b64_tr_b16 v[172:173], v162 offset:29696
	ds_read_b64_tr_b16 v[174:175], v162 offset:31232
	v_exp_f32_e32 v124, v84
	v_exp_f32_e32 v125, v85
	v_exp_f32_e32 v126, v86
	v_add_f32_e32 v224, v124, v125
	s_waitcnt lgkmcnt(4)
	v_mfma_f32_32x32x16_bf16 v[4:19], v[164:167], v[144:147], v[4:19]
	v_exp_f32_e32 v127, v87
	v_cvt_pk_bf16_f32 v184, v124, v125
	v_mov_b32_e32 v254, v224
	v_exp_f32_e32 v128, v88
	s_waitcnt lgkmcnt(2)
	v_mfma_f32_32x32x16_bf16 v[20:35], v[168:171], v[144:147], v[20:35]
	ds_read_b64_tr_b16 v[176:177], v162 offset:29760
	ds_read_b64_tr_b16 v[178:179], v162 offset:31296
	v_add_f32_e32 v226, v126, v127
	v_exp_f32_e32 v129, v89
	v_cvt_pk_bf16_f32 v185, v126, v127
	v_add_f32_e32 v254, v254, v226
	s_waitcnt lgkmcnt(2)
	v_mfma_f32_32x32x16_bf16 v[4:19], v[172:175], v[140:143], v[4:19]
	ds_read_b64_tr_b16 v[164:165], v162 offset:32768
	ds_read_b64_tr_b16 v[166:167], v162 offset:34304
	v_exp_f32_e32 v130, v90
	v_add_f32_e32 v233, v128, v129
	v_exp_f32_e32 v131, v91
	v_cvt_pk_bf16_f32 v186, v128, v129
	s_waitcnt lgkmcnt(2)
	v_mfma_f32_32x32x16_bf16 v[20:35], v[176:179], v[140:143], v[20:35]
	ds_read_b64_tr_b16 v[168:169], v162 offset:32832
	ds_read_b64_tr_b16 v[170:171], v162 offset:34368
	v_add_f32_e32 v254, v254, v233
	v_exp_f32_e32 v124, v92
	v_add_f32_e32 v224, v130, v131
	v_exp_f32_e32 v125, v93
	s_waitcnt lgkmcnt(2)
	v_mfma_f32_32x32x16_bf16 v[4:19], v[164:167], v[136:139], v[4:19]
	ds_read_b64_tr_b16 v[172:173], v162 offset:35840
	ds_read_b64_tr_b16 v[174:175], v162 offset:37376
	v_cvt_pk_bf16_f32 v187, v130, v131
	v_add_f32_e32 v254, v254, v224
	v_exp_f32_e32 v126, v94
	v_add_f32_e32 v226, v124, v125
	s_waitcnt lgkmcnt(2)
	v_mfma_f32_32x32x16_bf16 v[20:35], v[168:171], v[136:139], v[20:35]
	ds_read_b64_tr_b16 v[176:177], v162 offset:35904
	ds_read_b64_tr_b16 v[178:179], v162 offset:37440
	v_exp_f32_e32 v127, v95
	v_cvt_pk_bf16_f32 v188, v124, v125
	v_add_f32_e32 v254, v254, v226
	v_exp_f32_e32 v128, v96
	s_waitcnt lgkmcnt(2)
	v_mfma_f32_32x32x16_bf16 v[4:19], v[172:175], v[132:135], v[4:19]
	ds_read_b128 v[180:183], v155 offset:0
	ds_read_b128 v[112:115], v155 offset:6656
	v_add_f32_e32 v233, v126, v127
	v_exp_f32_e32 v129, v97
	v_cvt_pk_bf16_f32 v189, v126, v127
	v_add_f32_e32 v254, v254, v233
	s_waitcnt lgkmcnt(2)
	v_mfma_f32_32x32x16_bf16 v[20:35], v[176:179], v[132:135], v[20:35]
	ds_read_b128 v[116:119], v155 offset:32
	ds_read_b128 v[120:123], v155 offset:6688
	v_exp_f32_e32 v130, v98
	v_add_f32_e32 v224, v128, v129
	v_exp_f32_e32 v131, v99
	v_cvt_pk_bf16_f32 v190, v128, v129
	s_waitcnt lgkmcnt(3)
	v_mfma_f32_32x32x16_bf16 v[52:67], v[180:183], v[200:203], v[234:249]
	ds_read_b128 v[180:183], v155 offset:64
	v_add_f32_e32 v254, v254, v224
	v_exp_f32_e32 v124, v36
	v_add_f32_e32 v226, v130, v131
	v_exp_f32_e32 v125, v37
	s_waitcnt lgkmcnt(3)
	v_mfma_f32_32x32x16_bf16 v[68:83], v[112:115], v[200:203], v[234:249]
	ds_read_b128 v[112:115], v155 offset:6720
	v_cvt_pk_bf16_f32 v191, v130, v131
	v_add_f32_e32 v254, v254, v226
	v_exp_f32_e32 v126, v38
	v_add_f32_e32 v233, v124, v125
	s_waitcnt lgkmcnt(3)
	v_mfma_f32_32x32x16_bf16 v[52:67], v[116:119], v[204:207], v[52:67]
	ds_read_b128 v[116:119], v155 offset:96
	v_exp_f32_e32 v127, v39
	v_cvt_pk_bf16_f32 v192, v124, v125
	v_add_f32_e32 v254, v254, v233
	v_exp_f32_e32 v128, v40
	s_waitcnt lgkmcnt(3)
	v_mfma_f32_32x32x16_bf16 v[68:83], v[120:123], v[204:207], v[68:83]
	ds_read_b128 v[120:123], v155 offset:6752
	v_add_f32_e32 v224, v126, v127
	v_exp_f32_e32 v129, v41
	v_cvt_pk_bf16_f32 v193, v126, v127
	v_add_f32_e32 v254, v254, v224
	s_waitcnt lgkmcnt(3)
	v_mfma_f32_32x32x16_bf16 v[52:67], v[180:183], v[208:211], v[52:67]
	ds_read_b128 v[180:183], v155 offset:128
	v_exp_f32_e32 v130, v42
	v_add_f32_e32 v226, v128, v129
	v_exp_f32_e32 v131, v43
	v_cvt_pk_bf16_f32 v194, v128, v129
	s_waitcnt lgkmcnt(3)
	v_mfma_f32_32x32x16_bf16 v[68:83], v[112:115], v[208:211], v[68:83]
	ds_read_b128 v[112:115], v155 offset:6784
	v_add_f32_e32 v254, v254, v226
	v_exp_f32_e32 v124, v44
	v_add_f32_e32 v233, v130, v131
	v_exp_f32_e32 v125, v45
	s_waitcnt lgkmcnt(3)
	v_mfma_f32_32x32x16_bf16 v[52:67], v[116:119], v[212:215], v[52:67]
	ds_read_b128 v[116:119], v155 offset:160
	v_cvt_pk_bf16_f32 v195, v130, v131
	v_add_f32_e32 v254, v254, v233
	v_exp_f32_e32 v126, v46
	v_add_f32_e32 v224, v124, v125
	s_waitcnt lgkmcnt(3)
	v_mfma_f32_32x32x16_bf16 v[68:83], v[120:123], v[212:215], v[68:83]
	ds_read_b128 v[120:123], v155 offset:6816
	v_exp_f32_e32 v127, v47
	v_cvt_pk_bf16_f32 v196, v124, v125
	v_add_f32_e32 v254, v254, v224
	v_exp_f32_e32 v128, v48
	s_waitcnt lgkmcnt(3)
	v_mfma_f32_32x32x16_bf16 v[52:67], v[180:183], v[216:219], v[52:67]
	v_add_f32_e32 v226, v126, v127
	v_exp_f32_e32 v129, v49
	v_cvt_pk_bf16_f32 v197, v126, v127
	v_add_f32_e32 v254, v254, v226
	s_waitcnt lgkmcnt(2)
	v_mfma_f32_32x32x16_bf16 v[68:83], v[112:115], v[216:219], v[68:83]
	v_exp_f32_e32 v130, v50
	v_add_f32_e32 v233, v128, v129
	v_exp_f32_e32 v131, v51
	v_cvt_pk_bf16_f32 v198, v128, v129
	s_waitcnt lgkmcnt(1)
	v_mfma_f32_32x32x16_bf16 v[52:67], v[116:119], v[250:253], v[52:67]
	v_add_f32_e32 v254, v254, v233
	v_add_f32_e32 v224, v130, v131
	v_cvt_pk_bf16_f32 v199, v130, v131
	v_add_f32_e32 v254, v254, v224
	s_waitcnt lgkmcnt(0)
	v_mfma_f32_32x32x16_bf16 v[68:83], v[120:123], v[250:253], v[68:83]
	v_cmp_lt_f32_e32 vcc, 0x43800000, v254
	s_cbranch_vccnz .LpfU_s0
.LpfU_b0:
	v_add_f32_e32 v152, v152, v254
	s_cmp_eq_u32 s5, 0
	s_cbranch_scc1 .LpfU_nr0
	s_nop 11
	v_pk_mul_f32 v[4:5], v[220:221], v[4:5] op_sel_hi:[0,1]
	v_pk_mul_f32 v[6:7], v[220:221], v[6:7] op_sel_hi:[0,1]
	v_pk_mul_f32 v[8:9], v[220:221], v[8:9] op_sel_hi:[0,1]
	v_pk_mul_f32 v[10:11], v[220:221], v[10:11] op_sel_hi:[0,1]
	v_pk_mul_f32 v[12:13], v[220:221], v[12:13] op_sel_hi:[0,1]
	v_pk_mul_f32 v[14:15], v[220:221], v[14:15] op_sel_hi:[0,1]
	v_pk_mul_f32 v[16:17], v[220:221], v[16:17] op_sel_hi:[0,1]
	v_pk_mul_f32 v[18:19], v[220:221], v[18:19] op_sel_hi:[0,1]
	v_pk_mul_f32 v[20:21], v[220:221], v[20:21] op_sel_hi:[0,1]
	v_pk_mul_f32 v[22:23], v[220:221], v[22:23] op_sel_hi:[0,1]
	v_pk_mul_f32 v[24:25], v[220:221], v[24:25] op_sel_hi:[0,1]
	v_pk_mul_f32 v[26:27], v[220:221], v[26:27] op_sel_hi:[0,1]
	v_pk_mul_f32 v[28:29], v[220:221], v[28:29] op_sel_hi:[0,1]
	v_pk_mul_f32 v[30:31], v[220:221], v[30:31] op_sel_hi:[0,1]
	v_pk_mul_f32 v[32:33], v[220:221], v[32:33] op_sel_hi:[0,1]
	v_pk_mul_f32 v[34:35], v[220:221], v[34:35] op_sel_hi:[0,1]
	v_sub_f32_e32 v52, v52, v222
	v_sub_f32_e32 v68, v68, v222
	v_sub_f32_e32 v53, v53, v222
	v_sub_f32_e32 v69, v69, v222
	v_sub_f32_e32 v54, v54, v222
	v_sub_f32_e32 v70, v70, v222
	v_sub_f32_e32 v55, v55, v222
	v_sub_f32_e32 v71, v71, v222
	v_sub_f32_e32 v56, v56, v222
	v_sub_f32_e32 v72, v72, v222
	v_sub_f32_e32 v57, v57, v222
	v_sub_f32_e32 v73, v73, v222
	v_sub_f32_e32 v58, v58, v222
	v_sub_f32_e32 v74, v74, v222
	v_sub_f32_e32 v59, v59, v222
	v_sub_f32_e32 v75, v75, v222
	v_sub_f32_e32 v60, v60, v222
	v_sub_f32_e32 v76, v76, v222
	v_sub_f32_e32 v61, v61, v222
	v_sub_f32_e32 v77, v77, v222
	v_sub_f32_e32 v62, v62, v222
	v_sub_f32_e32 v78, v78, v222
	v_sub_f32_e32 v63, v63, v222
	v_sub_f32_e32 v79, v79, v222
	v_sub_f32_e32 v64, v64, v222
	v_sub_f32_e32 v80, v80, v222
	v_sub_f32_e32 v65, v65, v222
	v_sub_f32_e32 v81, v81, v222
	v_sub_f32_e32 v66, v66, v222
	v_sub_f32_e32 v82, v82, v222
	v_sub_f32_e32 v67, v67, v222
	v_sub_f32_e32 v83, v83, v222
	v_sub_f32_e32 v234, v234, v222
	v_sub_f32_e32 v235, v235, v222
	v_sub_f32_e32 v236, v236, v222
	v_sub_f32_e32 v237, v237, v222
	v_sub_f32_e32 v238, v238, v222
	v_sub_f32_e32 v239, v239, v222
	v_sub_f32_e32 v240, v240, v222
	v_sub_f32_e32 v241, v241, v222
	v_sub_f32_e32 v242, v242, v222
	v_sub_f32_e32 v243, v243, v222
	v_sub_f32_e32 v244, v244, v222
	v_sub_f32_e32 v245, v245, v222
	v_sub_f32_e32 v246, v246, v222
	v_sub_f32_e32 v247, v247, v222
	v_sub_f32_e32 v248, v248, v222
	v_sub_f32_e32 v249, v249, v222
.LpfU_nr0:
	s_waitcnt vmcnt(1)
	ds_write_b128 v157, v[104:107] offset:13312
	ds_write_b64 v158, v[108:109] offset:13440
	s_waitcnt vmcnt(0)
	ds_write_b128 v151, v[100:103] offset:38912
	s_waitcnt lgkmcnt(0)
	s_barrier
	s_mov_b32 s5, 0
	buffer_load_dwordx2 v[108:109], v161, s[12:15], s52 offen
	s_add_i32 s3, s53, 0xfe040000
	buffer_load_dwordx4 v[104:107], v150, s[12:15], s3 offen
	buffer_load_dwordx4 v[100:103], v150, s[12:15], s53 offen
	ds_read_b64_tr_b16 v[164:165], v162 offset:38912
	ds_read_b64_tr_b16 v[166:167], v162 offset:40448
	ds_read_b64_tr_b16 v[168:169], v162 offset:38976
	ds_read_b64_tr_b16 v[170:171], v162 offset:40512
	ds_read_b64_tr_b16 v[172:173], v162 offset:41984
	ds_read_b64_tr_b16 v[174:175], v162 offset:43520
	v_exp_f32_e32 v124, v52
	v_exp_f32_e32 v125, v53
	v_exp_f32_e32 v126, v54
	v_add_f32_e32 v224, v124, v125
	s_waitcnt lgkmcnt(4)
	v_mfma_f32_32x32x16_bf16 v[4:19], v[164:167], v[184:187], v[4:19]
	v_exp_f32_e32 v127, v55
	v_cvt_pk_bf16_f32 v144, v124, v125
	v_mov_b32_e32 v254, v224
	v_exp_f32_e32 v128, v56
	s_waitcnt lgkmcnt(2)
	v_mfma_f32_32x32x16_bf16 v[20:35], v[168:171], v[184:187], v[20:35]
	ds_read_b64_tr_b16 v[176:177], v162 offset:42048
	ds_read_b64_tr_b16 v[178:179], v162 offset:43584
	v_add_f32_e32 v226, v126, v127
	v_exp_f32_e32 v129, v57
	v_cvt_pk_bf16_f32 v145, v126, v127
	v_add_f32_e32 v254, v254, v226
	s_waitcnt lgkmcnt(2)
	v_mfma_f32_32x32x16_bf16 v[4:19], v[172:175], v[188:191], v[4:19]
	ds_read_b64_tr_b16 v[164:165], v162 offset:45056
	ds_read_b64_tr_b16 v[166:167], v162 offset:46592
	v_exp_f32_e32 v130, v58
	v_add_f32_e32 v233, v128, v129
	v_exp_f32_e32 v131, v59
	v_cvt_pk_bf16_f32 v146, v128, v129
	s_waitcnt lgkmcnt(2)
	v_mfma_f32_32x32x16_bf16 v[20:35], v[176:179], v[188:191], v[20:35]
	ds_read_b64_tr_b16 v[168:169], v162 offset:45120
	ds_read_b64_tr_b16 v[170:171], v162 offset:46656
	v_add_f32_e32 v254, v254, v233
	v_exp_f32_e32 v124, v60
	v_add_f32_e32 v224, v130, v131
	v_exp_f32_e32 v125, v61
	s_waitcnt lgkmcnt(2)
	v_mfma_f32_32x32x16_bf16 v[4:19], v[164:167], v[192:195], v[4:19]
	ds_read_b64_tr_b16 v[172:173], v162 offset:48128
	ds_read_b64_tr_b16 v[174:175], v162 offset:49664
	v_cvt_pk_bf16_f32 v147, v130, v131
	v_add_f32_e32 v254, v254, v224
	v_exp_f32_e32 v126, v62
	v_add_f32_e32 v226, v124, v125
	s_waitcnt lgkmcnt(2)
	v_mfma_f32_32x32x16_bf16 v[20:35], v[168:171], v[192:195], v[20:35]
	ds_read_b64_tr_b16 v[176:177], v162 offset:48192
	ds_read_b64_tr_b16 v[178:179], v162 offset:49728
	v_exp_f32_e32 v127, v63
	v_cvt_pk_bf16_f32 v140, v124, v125
	v_add_f32_e32 v254, v254, v226
	v_exp_f32_e32 v128, v64
	s_waitcnt lgkmcnt(2)
	v_mfma_f32_32x32x16_bf16 v[4:19], v[172:175], v[196:199], v[4:19]
	ds_read_b128 v[180:183], v155 offset:13312
	ds_read_b128 v[112:115], v155 offset:19968
	v_add_f32_e32 v233, v126, v127
	v_exp_f32_e32 v129, v65
	v_cvt_pk_bf16_f32 v141, v126, v127
	v_add_f32_e32 v254, v254, v233
	s_waitcnt lgkmcnt(2)
	v_mfma_f32_32x32x16_bf16 v[20:35], v[176:179], v[196:199], v[20:35]
	ds_read_b128 v[116:119], v155 offset:13344
	ds_read_b128 v[120:123], v155 offset:20000
	v_exp_f32_e32 v130, v66
	v_add_f32_e32 v224, v128, v129
	v_exp_f32_e32 v131, v67
	v_cvt_pk_bf16_f32 v142, v128, v129
	s_waitcnt lgkmcnt(3)
	v_mfma_f32_32x32x16_bf16 v[84:99], v[180:183], v[200:203], v[234:249]
	ds_read_b128 v[180:183], v155 offset:13376
	v_add_f32_e32 v254, v254, v224
	v_exp_f32_e32 v124, v68
	v_add_f32_e32 v226, v130, v131
	v_exp_f32_e32 v125, v69
	s_waitcnt lgkmcnt(3)
	v_mfma_f32_32x32x16_bf16 v[36:51], v[112:115], v[200:203], v[234:249]
	ds_read_b128 v[112:115], v155 offset:20032
	v_cvt_pk_bf16_f32 v143, v130, v131
	v_add_f32_e32 v254, v254, v226
	v_exp_f32_e32 v126, v70
	v_add_f32_e32 v233, v124, v125
	s_waitcnt lgkmcnt(3)
	v_mfma_f32_32x32x16_bf16 v[84:99], v[116:119], v[204:207], v[84:99]
	ds_read_b128 v[116:119], v155 offset:13408
	v_exp_f32_e32 v127, v71
	v_cvt_pk_bf16_f32 v136, v124, v125
	v_add_f32_e32 v254, v254, v233
	v_exp_f32_e32 v128, v72
	s_waitcnt lgkmcnt(3)
	v_mfma_f32_32x32x16_bf16 v[36:51], v[120:123], v[204:207], v[36:51]
	ds_read_b128 v[120:123], v155 offset:20064
	v_add_f32_e32 v224, v126, v127
	v_exp_f32_e32 v129, v73
	v_cvt_pk_bf16_f32 v137, v126, v127
	v_add_f32_e32 v254, v254, v224
	s_waitcnt lgkmcnt(3)
	v_mfma_f32_32x32x16_bf16 v[84:99], v[180:183], v[208:211], v[84:99]
	ds_read_b128 v[180:183], v155 offset:13440
	v_exp_f32_e32 v130, v74
	v_add_f32_e32 v226, v128, v129
	v_exp_f32_e32 v131, v75
	v_cvt_pk_bf16_f32 v138, v128, v129
	s_waitcnt lgkmcnt(3)
	v_mfma_f32_32x32x16_bf16 v[36:51], v[112:115], v[208:211], v[36:51]
	ds_read_b128 v[112:115], v155 offset:20096
	v_add_f32_e32 v254, v254, v226
	v_exp_f32_e32 v124, v76
	v_add_f32_e32 v233, v130, v131
	v_exp_f32_e32 v125, v77
	s_waitcnt lgkmcnt(3)
	v_mfma_f32_32x32x16_bf16 v[84:99], v[116:119], v[212:215], v[84:99]
	ds_read_b128 v[116:119], v155 offset:13472
	v_cvt_pk_bf16_f32 v139, v130, v131
	v_add_f32_e32 v254, v254, v233
	v_exp_f32_e32 v126, v78
	v_add_f32_e32 v224, v124, v125
	s_waitcnt lgkmcnt(3)
	v_mfma_f32_32x32x16_bf16 v[36:51], v[120:123], v[212:215], v[36:51]
	ds_read_b128 v[120:123], v155 offset:20128
	v_exp_f32_e32 v127, v79
	v_cvt_pk_bf16_f32 v132, v124, v125
	v_add_f32_e32 v254, v254, v224
	v_exp_f32_e32 v128, v80
	s_waitcnt lgkmcnt(3)
	v_mfma_f32_32x32x16_bf16 v[84:99], v[180:183], v[216:219], v[84:99]
	v_add_f32_e32 v226, v126, v127
	v_exp_f32_e32 v129, v81
	v_cvt_pk_bf16_f32 v133, v126, v127
	v_add_f32_e32 v254, v254, v226
	s_waitcnt lgkmcnt(2)
	v_mfma_f32_32x32x16_bf16 v[36:51], v[112:115], v[216:219], v[36:51]
	v_exp_f32_e32 v130, v82
	v_add_f32_e32 v233, v128, v129
	v_exp_f32_e32 v131, v83
	v_cvt_pk_bf16_f32 v134, v128, v129
	s_waitcnt lgkmcnt(1)
	v_mfma_f32_32x32x16_bf16 v[84:99], v[116:119], v[250:253], v[84:99]
	v_add_f32_e32 v254, v254, v233
	v_add_f32_e32 v224, v130, v131
	v_cvt_pk_bf16_f32 v135, v130, v131
	v_add_f32_e32 v254, v254, v224
	s_waitcnt lgkmcnt(0)
	v_mfma_f32_32x32x16_bf16 v[36:51], v[120:123], v[250:253], v[36:51]
	v_cmp_lt_f32_e32 vcc, 0x43800000, v254
	s_cbranch_vccnz .LpfU_s1
.LpfU_b1:
	v_add_f32_e32 v152, v152, v254
	s_cmp_eq_u32 s5, 0
	s_cbranch_scc1 .LpfU_nr1
	s_nop 11
	v_pk_mul_f32 v[4:5], v[220:221], v[4:5] op_sel_hi:[0,1]
	v_pk_mul_f32 v[6:7], v[220:221], v[6:7] op_sel_hi:[0,1]
	v_pk_mul_f32 v[8:9], v[220:221], v[8:9] op_sel_hi:[0,1]
	v_pk_mul_f32 v[10:11], v[220:221], v[10:11] op_sel_hi:[0,1]
	v_pk_mul_f32 v[12:13], v[220:221], v[12:13] op_sel_hi:[0,1]
	v_pk_mul_f32 v[14:15], v[220:221], v[14:15] op_sel_hi:[0,1]
	v_pk_mul_f32 v[16:17], v[220:221], v[16:17] op_sel_hi:[0,1]
	v_pk_mul_f32 v[18:19], v[220:221], v[18:19] op_sel_hi:[0,1]
	v_pk_mul_f32 v[20:21], v[220:221], v[20:21] op_sel_hi:[0,1]
	v_pk_mul_f32 v[22:23], v[220:221], v[22:23] op_sel_hi:[0,1]
	v_pk_mul_f32 v[24:25], v[220:221], v[24:25] op_sel_hi:[0,1]
	v_pk_mul_f32 v[26:27], v[220:221], v[26:27] op_sel_hi:[0,1]
	v_pk_mul_f32 v[28:29], v[220:221], v[28:29] op_sel_hi:[0,1]
	v_pk_mul_f32 v[30:31], v[220:221], v[30:31] op_sel_hi:[0,1]
	v_pk_mul_f32 v[32:33], v[220:221], v[32:33] op_sel_hi:[0,1]
	v_pk_mul_f32 v[34:35], v[220:221], v[34:35] op_sel_hi:[0,1]
	v_sub_f32_e32 v84, v84, v222
	v_sub_f32_e32 v36, v36, v222
	v_sub_f32_e32 v85, v85, v222
	v_sub_f32_e32 v37, v37, v222
	v_sub_f32_e32 v86, v86, v222
	v_sub_f32_e32 v38, v38, v222
	v_sub_f32_e32 v87, v87, v222
	v_sub_f32_e32 v39, v39, v222
	v_sub_f32_e32 v88, v88, v222
	v_sub_f32_e32 v40, v40, v222
	v_sub_f32_e32 v89, v89, v222
	v_sub_f32_e32 v41, v41, v222
	v_sub_f32_e32 v90, v90, v222
	v_sub_f32_e32 v42, v42, v222
	v_sub_f32_e32 v91, v91, v222
	v_sub_f32_e32 v43, v43, v222
	v_sub_f32_e32 v92, v92, v222
	v_sub_f32_e32 v44, v44, v222
	v_sub_f32_e32 v93, v93, v222
	v_sub_f32_e32 v45, v45, v222
	v_sub_f32_e32 v94, v94, v222
	v_sub_f32_e32 v46, v46, v222
	v_sub_f32_e32 v95, v95, v222
	v_sub_f32_e32 v47, v47, v222
	v_sub_f32_e32 v96, v96, v222
	v_sub_f32_e32 v48, v48, v222
	v_sub_f32_e32 v97, v97, v222
	v_sub_f32_e32 v49, v49, v222
	v_sub_f32_e32 v98, v98, v222
	v_sub_f32_e32 v50, v50, v222
	v_sub_f32_e32 v99, v99, v222
	v_sub_f32_e32 v51, v51, v222
	v_sub_f32_e32 v234, v234, v222
	v_sub_f32_e32 v235, v235, v222
	v_sub_f32_e32 v236, v236, v222
	v_sub_f32_e32 v237, v237, v222
	v_sub_f32_e32 v238, v238, v222
	v_sub_f32_e32 v239, v239, v222
	v_sub_f32_e32 v240, v240, v222
	v_sub_f32_e32 v241, v241, v222
	v_sub_f32_e32 v242, v242, v222
	v_sub_f32_e32 v243, v243, v222
	v_sub_f32_e32 v244, v244, v222
	v_sub_f32_e32 v245, v245, v222
	v_sub_f32_e32 v246, v246, v222
	v_sub_f32_e32 v247, v247, v222
	v_sub_f32_e32 v248, v248, v222
	v_sub_f32_e32 v249, v249, v222

.Lpe_exit:
	v_add_f32_e32 v84, v84, v159
	v_add_f32_e32 v36, v36, v159
	v_add_f32_e32 v85, v85, v159
	v_add_f32_e32 v37, v37, v159
	v_add_f32_e32 v86, v86, v159
	v_add_f32_e32 v38, v38, v159
	v_add_f32_e32 v87, v87, v159
	v_add_f32_e32 v39, v39, v159
	v_add_f32_e32 v88, v88, v159
	v_add_f32_e32 v40, v40, v159
	v_add_f32_e32 v89, v89, v159
	v_add_f32_e32 v41, v41, v159
	v_add_f32_e32 v90, v90, v159
	v_add_f32_e32 v42, v42, v159
	v_add_f32_e32 v91, v91, v159
	v_add_f32_e32 v43, v43, v159
	v_add_f32_e32 v92, v92, v159
	v_add_f32_e32 v44, v44, v159
	v_add_f32_e32 v93, v93, v159
	v_add_f32_e32 v45, v45, v159
	v_add_f32_e32 v94, v94, v159
	v_add_f32_e32 v46, v46, v159
	v_add_f32_e32 v95, v95, v159
	v_add_f32_e32 v47, v47, v159
	v_add_f32_e32 v96, v96, v159
	v_add_f32_e32 v48, v48, v159
	v_add_f32_e32 v97, v97, v159
	v_add_f32_e32 v49, v49, v159
	v_add_f32_e32 v98, v98, v159
	v_add_f32_e32 v50, v50, v159
	v_add_f32_e32 v99, v99, v159
	v_add_f32_e32 v51, v51, v159
	s_branch .LBB0_860
.LpfU_s0:
	v_max3_f32 v2, v84, v36, v85
	v_max3_f32 v110, v37, v86, v38
	v_max3_f32 v2, v2, v87, v39
	v_max3_f32 v110, v110, v88, v40
	v_max3_f32 v2, v2, v89, v41
	v_max3_f32 v110, v110, v90, v42
	v_max3_f32 v2, v2, v91, v43
	v_max3_f32 v110, v110, v92, v44
	v_max3_f32 v2, v2, v93, v45
	v_max3_f32 v110, v110, v94, v46
	v_max3_f32 v2, v2, v95, v47
	v_max3_f32 v110, v110, v96, v48
	v_max3_f32 v2, v2, v97, v49
	v_max3_f32 v110, v110, v98, v50
	v_max3_f32 v2, v2, v110, v99
	v_max_f32_e32 v2, v2, v51
	v_mov_b32_e32 v111, v2
	s_nop 1
	v_permlane32_swap_b32_e32 v2, v111
	v_max_f32_e32 v2, v2, v111
	v_max_f32_e32 v222, 0, v2
	s_mov_b32 s5, 1
	v_exp_f32_e64 v220, -v222
	v_add_f32_e32 v159, v159, v222
	v_sub_f32_e32 v84, v84, v222
	v_sub_f32_e32 v36, v36, v222
	v_sub_f32_e32 v85, v85, v222
	v_sub_f32_e32 v37, v37, v222
	v_sub_f32_e32 v86, v86, v222
	v_sub_f32_e32 v38, v38, v222
	v_sub_f32_e32 v87, v87, v222
	v_sub_f32_e32 v39, v39, v222
	v_sub_f32_e32 v88, v88, v222
	v_sub_f32_e32 v40, v40, v222
	v_sub_f32_e32 v89, v89, v222
	v_sub_f32_e32 v41, v41, v222
	v_sub_f32_e32 v90, v90, v222
	v_sub_f32_e32 v42, v42, v222
	v_sub_f32_e32 v91, v91, v222
	v_sub_f32_e32 v43, v43, v222
	v_sub_f32_e32 v92, v92, v222
	v_sub_f32_e32 v44, v44, v222
	v_sub_f32_e32 v93, v93, v222
	v_sub_f32_e32 v45, v45, v222
	v_sub_f32_e32 v94, v94, v222
	v_sub_f32_e32 v46, v46, v222
	v_sub_f32_e32 v95, v95, v222
	v_sub_f32_e32 v47, v47, v222
	v_sub_f32_e32 v96, v96, v222
	v_sub_f32_e32 v48, v48, v222
	v_sub_f32_e32 v97, v97, v222
	v_sub_f32_e32 v49, v49, v222
	v_sub_f32_e32 v98, v98, v222
	v_sub_f32_e32 v50, v50, v222
	v_sub_f32_e32 v99, v99, v222
	v_sub_f32_e32 v51, v51, v222
	v_mul_f32_e32 v152, v152, v220
	v_exp_f32_e32 v124, v84
	v_exp_f32_e32 v125, v85
	s_nop 0
	v_add_f32_e32 v111, v124, v125
	v_cvt_pk_bf16_f32 v184, v124, v125
	v_mov_b32_e32 v254, v111
	v_exp_f32_e32 v126, v86
	v_exp_f32_e32 v127, v87
	s_nop 0
	v_add_f32_e32 v111, v126, v127
	v_cvt_pk_bf16_f32 v185, v126, v127
	v_add_f32_e32 v254, v254, v111
	v_exp_f32_e32 v128, v88
	v_exp_f32_e32 v129, v89
	s_nop 0
	v_add_f32_e32 v111, v128, v129
	v_cvt_pk_bf16_f32 v186, v128, v129
	v_add_f32_e32 v254, v254, v111
	v_exp_f32_e32 v130, v90
	v_exp_f32_e32 v131, v91
	s_nop 0
	v_add_f32_e32 v111, v130, v131
	v_cvt_pk_bf16_f32 v187, v130, v131
	v_add_f32_e32 v254, v254, v111
	v_exp_f32_e32 v124, v92
	v_exp_f32_e32 v125, v93
	s_nop 0
	v_add_f32_e32 v111, v124, v125
	v_cvt_pk_bf16_f32 v188, v124, v125
	v_add_f32_e32 v254, v254, v111
	v_exp_f32_e32 v126, v94
	v_exp_f32_e32 v127, v95
	s_nop 0
	v_add_f32_e32 v111, v126, v127
	v_cvt_pk_bf16_f32 v189, v126, v127
	v_add_f32_e32 v254, v254, v111
	v_exp_f32_e32 v128, v96
	v_exp_f32_e32 v129, v97
	s_nop 0
	v_add_f32_e32 v111, v128, v129
	v_cvt_pk_bf16_f32 v190, v128, v129
	v_add_f32_e32 v254, v254, v111
	v_exp_f32_e32 v130, v98
	v_exp_f32_e32 v131, v99
	s_nop 0
	v_add_f32_e32 v111, v130, v131
	v_cvt_pk_bf16_f32 v191, v130, v131
	v_add_f32_e32 v254, v254, v111
	v_exp_f32_e32 v124, v36
	v_exp_f32_e32 v125, v37
	s_nop 0
	v_add_f32_e32 v111, v124, v125
	v_cvt_pk_bf16_f32 v192, v124, v125
	v_add_f32_e32 v254, v254, v111
	v_exp_f32_e32 v126, v38
	v_exp_f32_e32 v127, v39
	s_nop 0
	v_add_f32_e32 v111, v126, v127
	v_cvt_pk_bf16_f32 v193, v126, v127
	v_add_f32_e32 v254, v254, v111
	v_exp_f32_e32 v128, v40
	v_exp_f32_e32 v129, v41
	s_nop 0
	v_add_f32_e32 v111, v128, v129
	v_cvt_pk_bf16_f32 v194, v128, v129
	v_add_f32_e32 v254, v254, v111
	v_exp_f32_e32 v130, v42
	v_exp_f32_e32 v131, v43
	s_nop 0
	v_add_f32_e32 v111, v130, v131
	v_cvt_pk_bf16_f32 v195, v130, v131
	v_add_f32_e32 v254, v254, v111
	v_exp_f32_e32 v124, v44
	v_exp_f32_e32 v125, v45
	s_nop 0
	v_add_f32_e32 v111, v124, v125
	v_cvt_pk_bf16_f32 v196, v124, v125
	v_add_f32_e32 v254, v254, v111
	v_exp_f32_e32 v126, v46
	v_exp_f32_e32 v127, v47
	s_nop 0
	v_add_f32_e32 v111, v126, v127
	v_cvt_pk_bf16_f32 v197, v126, v127
	v_add_f32_e32 v254, v254, v111
	v_exp_f32_e32 v128, v48
	v_exp_f32_e32 v129, v49
	s_nop 0
	v_add_f32_e32 v111, v128, v129
	v_cvt_pk_bf16_f32 v198, v128, v129
	v_add_f32_e32 v254, v254, v111
	v_exp_f32_e32 v130, v50
	v_exp_f32_e32 v131, v51
	s_nop 0
	v_add_f32_e32 v111, v130, v131
	v_cvt_pk_bf16_f32 v199, v130, v131
	v_add_f32_e32 v254, v254, v111
	s_branch .LpfU_b0
.LpfU_s1:
	v_max3_f32 v2, v52, v68, v53
	v_max3_f32 v110, v69, v54, v70
	v_max3_f32 v2, v2, v55, v71
	v_max3_f32 v110, v110, v56, v72
	v_max3_f32 v2, v2, v57, v73
	v_max3_f32 v110, v110, v58, v74
	v_max3_f32 v2, v2, v59, v75
	v_max3_f32 v110, v110, v60, v76
	v_max3_f32 v2, v2, v61, v77
	v_max3_f32 v110, v110, v62, v78
	v_max3_f32 v2, v2, v63, v79
	v_max3_f32 v110, v110, v64, v80
	v_max3_f32 v2, v2, v65, v81
	v_max3_f32 v110, v110, v66, v82
	v_max3_f32 v2, v2, v110, v67
	v_max_f32_e32 v2, v2, v83
	v_mov_b32_e32 v111, v2
	s_nop 1
	v_permlane32_swap_b32_e32 v2, v111
	v_max_f32_e32 v2, v2, v111
	v_max_f32_e32 v222, 0, v2
	s_mov_b32 s5, 1
	v_exp_f32_e64 v220, -v222
	v_add_f32_e32 v159, v159, v222
	v_sub_f32_e32 v52, v52, v222
	v_sub_f32_e32 v68, v68, v222
	v_sub_f32_e32 v53, v53, v222
	v_sub_f32_e32 v69, v69, v222
	v_sub_f32_e32 v54, v54, v222
	v_sub_f32_e32 v70, v70, v222
	v_sub_f32_e32 v55, v55, v222
	v_sub_f32_e32 v71, v71, v222
	v_sub_f32_e32 v56, v56, v222
	v_sub_f32_e32 v72, v72, v222
	v_sub_f32_e32 v57, v57, v222
	v_sub_f32_e32 v73, v73, v222
	v_sub_f32_e32 v58, v58, v222
	v_sub_f32_e32 v74, v74, v222
	v_sub_f32_e32 v59, v59, v222
	v_sub_f32_e32 v75, v75, v222
	v_sub_f32_e32 v60, v60, v222
	v_sub_f32_e32 v76, v76, v222
	v_sub_f32_e32 v61, v61, v222
	v_sub_f32_e32 v77, v77, v222
	v_sub_f32_e32 v62, v62, v222
	v_sub_f32_e32 v78, v78, v222
	v_sub_f32_e32 v63, v63, v222
	v_sub_f32_e32 v79, v79, v222
	v_sub_f32_e32 v64, v64, v222
	v_sub_f32_e32 v80, v80, v222
	v_sub_f32_e32 v65, v65, v222
	v_sub_f32_e32 v81, v81, v222
	v_sub_f32_e32 v66, v66, v222
	v_sub_f32_e32 v82, v82, v222
	v_sub_f32_e32 v67, v67, v222
	v_sub_f32_e32 v83, v83, v222
	v_mul_f32_e32 v152, v152, v220
	v_exp_f32_e32 v124, v52
	v_exp_f32_e32 v125, v53
	s_nop 0
	v_add_f32_e32 v111, v124, v125
	v_cvt_pk_bf16_f32 v144, v124, v125
	v_mov_b32_e32 v254, v111
	v_exp_f32_e32 v126, v54
	v_exp_f32_e32 v127, v55
	s_nop 0
	v_add_f32_e32 v111, v126, v127
	v_cvt_pk_bf16_f32 v145, v126, v127
	v_add_f32_e32 v254, v254, v111
	v_exp_f32_e32 v128, v56
	v_exp_f32_e32 v129, v57
	s_nop 0
	v_add_f32_e32 v111, v128, v129
	v_cvt_pk_bf16_f32 v146, v128, v129
	v_add_f32_e32 v254, v254, v111
	v_exp_f32_e32 v130, v58
	v_exp_f32_e32 v131, v59
	s_nop 0
	v_add_f32_e32 v111, v130, v131
	v_cvt_pk_bf16_f32 v147, v130, v131
	v_add_f32_e32 v254, v254, v111
	v_exp_f32_e32 v124, v60
	v_exp_f32_e32 v125, v61
	s_nop 0
	v_add_f32_e32 v111, v124, v125
	v_cvt_pk_bf16_f32 v140, v124, v125
	v_add_f32_e32 v254, v254, v111
	v_exp_f32_e32 v126, v62
	v_exp_f32_e32 v127, v63
	s_nop 0
	v_add_f32_e32 v111, v126, v127
	v_cvt_pk_bf16_f32 v141, v126, v127
	v_add_f32_e32 v254, v254, v111
	v_exp_f32_e32 v128, v64
	v_exp_f32_e32 v129, v65
	s_nop 0
	v_add_f32_e32 v111, v128, v129
	v_cvt_pk_bf16_f32 v142, v128, v129
	v_add_f32_e32 v254, v254, v111
	v_exp_f32_e32 v130, v66
	v_exp_f32_e32 v131, v67
	s_nop 0
	v_add_f32_e32 v111, v130, v131
	v_cvt_pk_bf16_f32 v143, v130, v131
	v_add_f32_e32 v254, v254, v111
	v_exp_f32_e32 v124, v68
	v_exp_f32_e32 v125, v69
	s_nop 0
	v_add_f32_e32 v111, v124, v125
	v_cvt_pk_bf16_f32 v136, v124, v125
	v_add_f32_e32 v254, v254, v111
	v_exp_f32_e32 v126, v70
	v_exp_f32_e32 v127, v71
	s_nop 0
	v_add_f32_e32 v111, v126, v127
	v_cvt_pk_bf16_f32 v137, v126, v127
	v_add_f32_e32 v254, v254, v111
	v_exp_f32_e32 v128, v72
	v_exp_f32_e32 v129, v73
	s_nop 0
	v_add_f32_e32 v111, v128, v129
	v_cvt_pk_bf16_f32 v138, v128, v129
	v_add_f32_e32 v254, v254, v111
	v_exp_f32_e32 v130, v74
	v_exp_f32_e32 v131, v75
	s_nop 0
	v_add_f32_e32 v111, v130, v131
	v_cvt_pk_bf16_f32 v139, v130, v131
	v_add_f32_e32 v254, v254, v111
	v_exp_f32_e32 v124, v76
	v_exp_f32_e32 v125, v77
	s_nop 0
	v_add_f32_e32 v111, v124, v125
	v_cvt_pk_bf16_f32 v132, v124, v125
	v_add_f32_e32 v254, v254, v111
	v_exp_f32_e32 v126, v78
	v_exp_f32_e32 v127, v79
	s_nop 0
	v_add_f32_e32 v111, v126, v127
	v_cvt_pk_bf16_f32 v133, v126, v127
	v_add_f32_e32 v254, v254, v111
	v_exp_f32_e32 v128, v80
	v_exp_f32_e32 v129, v81
	s_nop 0
	v_add_f32_e32 v111, v128, v129
	v_cvt_pk_bf16_f32 v134, v128, v129
	v_add_f32_e32 v254, v254, v111
	v_exp_f32_e32 v130, v82
	v_exp_f32_e32 v131, v83
	s_nop 0
	v_add_f32_e32 v111, v130, v131
	v_cvt_pk_bf16_f32 v135, v130, v131
	v_add_f32_e32 v254, v254, v111
	s_branch .LpfU_b1
